# v_full11 + accumulator clears as 64-bit moves (v_mov_b64 of inline 0) instead of per-dword moves
# baseline (speedup 1.0000x reference)
.LBB0_291:
	v_and_b32_e32 v27, 15, v26
	v_and_b32_e32 v28, 48, v26
	v_lshlrev_b32_e32 v27, 6, v27
	v_lshlrev_b32_e32 v26, 2, v26
	s_lshl_b32 s25, s25, 12
	s_add_i32 m0, s30, 0x18000
	v_lshl_add_u64 v[8:9], v[8:9], 0, s[36:37]
	v_or_b32_e32 v29, v27, v28
	v_and_b32_e32 v26, 32, v26
	s_lshl_b32 s24, s24, 13
	s_and_b32 s25, s25, 0x3000
	s_waitcnt vmcnt(2)
	s_barrier
	global_load_lds_dwordx4 v[8:9], off
	v_lshl_add_u64 v[6:7], v[6:7], 0, s[36:37]
	s_add_i32 m0, s30, 0x1a000
	s_add_i32 s47, s30, 0x8000
	s_add_i32 s48, s30, 0xa000
	v_bitop3_b32 v27, v27, v26, v28 bitop3:0x36
	v_bitop3_b32 v26, v29, s24, v26 bitop3:0xde
	global_load_lds_dwordx4 v[6:7], off
	v_lshl_add_u64 v[4:5], v[4:5], 0, s[36:37]
	s_mov_b32 m0, s47
	s_add_u32 s24, s38, 0x20080
	v_or_b32_e32 v142, s25, v27
	global_load_lds_dwordx4 v[4:5], off
	v_lshl_add_u64 v[2:3], v[2:3], 0, s[36:37]
	s_mov_b32 m0, s48
	s_addc_u32 s25, s39, 0
	global_load_lds_dwordx4 v[2:3], off
	s_add_i32 m0, s30, 0x1c000
	v_lshl_add_u64 v[2:3], s[24:25], 0, v[112:113]
	global_load_lds_dwordx4 v[2:3], off
	v_lshl_add_u64 v[0:1], s[24:25], 0, v[0:1]
	s_add_i32 m0, s30, 0x1e000
	v_readlane_b32 s24, v252, 13
	global_load_lds_dwordx4 v[0:1], off
	v_lshlrev_b32_e32 v0, 12, v18
	v_and_b32_e32 v0, 0x7fffe000, v0
	v_lshl_add_u32 v0, v19, 9, v0
	v_or_b32_e32 v0, v0, v20
	v_add_lshl_u32 v112, v0, v21, 1
	v_lshlrev_b32_e32 v0, 12, v22
	v_and_b32_e32 v0, 0x7fffe000, v0
	v_readlane_b32 s25, v252, 14
	s_add_u32 s12, s24, s12
	v_lshl_add_u32 v0, v23, 9, v0
	s_addc_u32 s13, s25, s13
	v_or_b32_e32 v0, v0, v24
	v_lshl_add_u64 v[134:135], s[12:13], 0, v[112:113]
	v_add_lshl_u32 v112, v0, v25, 1
	v_lshlrev_b32_e32 v0, 17, v10
	v_and_b32_e32 v0, 0x7ffc0000, v0
	v_lshl_add_u32 v0, v11, 14, v0
	v_or_b32_e32 v0, v0, v12
	v_lshl_add_u64 v[136:137], s[12:13], 0, v[112:113]
	v_add_lshl_u32 v112, v0, v13, 1
	v_lshlrev_b32_e32 v0, 17, v14
	v_and_b32_e32 v0, 0x7ffc0000, v0
	s_add_u32 s6, s8, s6
	v_lshl_add_u32 v0, v15, 14, v0
	s_waitcnt vmcnt(6)
	s_addc_u32 s7, s9, s7
	v_or_b32_e32 v0, v0, v16
	v_lshl_add_u64 v[138:139], s[6:7], 0, v[112:113]
	v_add_lshl_u32 v112, v0, v17, 1
	v_mov_b32_e32 v0, 0
	v_lshl_add_u64 v[140:141], s[6:7], 0, v[112:113]
	s_mov_b32 s6, -2
	v_add_u32_e32 v112, 0, v26
	v_mov_b32_e32 v1, 0
	v_mov_b64_e32 v[2:3], 0
	v_mov_b64_e32 v[4:5], 0
	v_mov_b64_e32 v[6:7], 0
	v_mov_b64_e32 v[8:9], 0
	v_mov_b64_e32 v[10:11], 0
	v_mov_b64_e32 v[12:13], 0
	v_mov_b64_e32 v[14:15], 0
	v_mov_b64_e32 v[16:17], 0
	v_mov_b64_e32 v[18:19], 0
	v_mov_b64_e32 v[20:21], 0
	v_mov_b64_e32 v[22:23], 0
	v_mov_b64_e32 v[24:25], 0
	v_mov_b64_e32 v[26:27], 0
	v_mov_b64_e32 v[28:29], 0
	v_mov_b64_e32 v[30:31], 0
	v_mov_b64_e32 v[32:33], 0
	v_mov_b64_e32 v[34:35], 0
	v_mov_b64_e32 v[36:37], 0
	v_mov_b64_e32 v[38:39], 0
	v_mov_b64_e32 v[40:41], 0
	v_mov_b64_e32 v[42:43], 0
	v_mov_b64_e32 v[44:45], 0
	v_mov_b64_e32 v[46:47], 0
	v_mov_b64_e32 v[48:49], 0
	v_mov_b64_e32 v[50:51], 0
	v_mov_b64_e32 v[52:53], 0
	v_mov_b64_e32 v[54:55], 0
	v_mov_b64_e32 v[56:57], 0
	v_mov_b64_e32 v[58:59], 0
	v_mov_b64_e32 v[60:61], 0
	v_mov_b64_e32 v[62:63], 0
	v_mov_b64_e32 v[68:69], 0
	v_mov_b64_e32 v[70:71], 0
	v_mov_b64_e32 v[80:81], 0
	v_mov_b64_e32 v[82:83], 0
	v_mov_b64_e32 v[84:85], 0
	v_mov_b64_e32 v[86:87], 0
	v_mov_b64_e32 v[88:89], 0
	v_mov_b64_e32 v[90:91], 0
	v_mov_b64_e32 v[92:93], 0
	v_mov_b64_e32 v[94:95], 0
	v_mov_b64_e32 v[96:97], 0
	v_mov_b64_e32 v[98:99], 0
	v_mov_b64_e32 v[100:101], 0
	v_mov_b64_e32 v[102:103], 0
	v_mov_b64_e32 v[104:105], 0
	v_mov_b64_e32 v[106:107], 0
	v_mov_b64_e32 v[108:109], 0
	v_mov_b64_e32 v[110:111], 0
	v_mov_b64_e32 v[114:115], 0
	v_mov_b64_e32 v[116:117], 0
	v_mov_b64_e32 v[118:119], 0
	v_mov_b64_e32 v[120:121], 0
	v_mov_b64_e32 v[122:123], 0
	v_mov_b64_e32 v[124:125], 0
	v_mov_b64_e32 v[126:127], 0
	v_mov_b64_e32 v[128:129], 0
	v_mov_b64_e32 v[64:65], 0
	v_mov_b64_e32 v[66:67], 0
	v_mov_b64_e32 v[72:73], 0
	v_mov_b64_e32 v[74:75], 0
	v_mov_b64_e32 v[76:77], 0
	v_mov_b64_e32 v[78:79], 0
	s_barrier

.LBB0_443:
	v_mov_b32_e32 v133, v113
	v_lshlrev_b32_e32 v0, 14, v0
	v_lshl_add_u64 v[12:13], s[4:5], 0, v[132:133]
	v_sub_u32_e32 v133, v130, v0
	v_lshlrev_b32_e32 v0, 14, v1
	v_sub_u32_e32 v141, v132, v0
	v_lshlrev_b32_e32 v0, 14, v2
	v_sub_u32_e32 v142, v134, v0
	v_lshlrev_b32_e32 v0, 14, v4
	v_mov_b32_e32 v139, v113
	v_sub_u32_e32 v140, v136, v0
	v_and_b32_e32 v0, 15, v3
	v_and_b32_e32 v1, 48, v3
	v_lshlrev_b32_e32 v3, 2, v3
	v_lshl_add_u64 v[144:145], s[2:3], 0, v[112:113]
	v_lshl_add_u64 v[164:165], s[2:3], 0, v[138:139]
	v_lshlrev_b32_e32 v0, 6, v0
	v_and_b32_e32 v3, 32, v3
	s_lshl_b32 s2, s7, 12
	v_lshl_add_u64 v[6:7], s[0:1], 0, v[112:113]
	v_or_b32_e32 v2, v0, v1
	v_bitop3_b32 v0, v0, v3, v1 bitop3:0x36
	s_and_b32 s2, s2, 0x3000
	v_lshl_add_u64 v[8:9], s[0:1], 0, v[138:139]
	v_mov_b32_e32 v131, v113
	v_or_b32_e32 v143, s2, v0
	s_add_i32 m0, s74, 0x18000
	v_lshl_add_u64 v[0:1], v[6:7], 0, s[36:37]
	s_ashr_i32 s96, s30, 31
	v_lshl_add_u64 v[10:11], s[4:5], 0, v[130:131]
	s_lshl_b32 s3, s6, 13
	s_waitcnt vmcnt(2)
	s_barrier
	global_load_lds_dwordx4 v[0:1], off
	v_lshl_add_u64 v[0:1], v[8:9], 0, s[36:37]
	s_add_i32 m0, s74, 0x1a000
	s_add_i32 s50, s74, 0x8000
	s_add_i32 s54, s74, 0xa000
	global_load_lds_dwordx4 v[0:1], off
	v_lshl_add_u64 v[0:1], v[10:11], 0, s[36:37]
	s_mov_b32 m0, s50
	s_add_u32 s2, s0, 0x18080
	v_bitop3_b32 v2, v2, s3, v3 bitop3:0xde
	global_load_lds_dwordx4 v[0:1], off
	v_lshl_add_u64 v[0:1], v[12:13], 0, s[36:37]
	s_mov_b32 m0, s54
	s_addc_u32 s3, s1, 0
	global_load_lds_dwordx4 v[0:1], off
	s_add_i32 m0, s74, 0x1c000
	v_lshl_add_u64 v[0:1], s[2:3], 0, v[112:113]
	global_load_lds_dwordx4 v[0:1], off
	v_lshl_add_u64 v[0:1], s[2:3], 0, v[138:139]
	s_add_i32 m0, s74, 0x1e000
	v_mov_b32_e32 v135, v113
	global_load_lds_dwordx4 v[0:1], off
	s_waitcnt vmcnt(6)
	v_mov_b32_e32 v0, 0
	v_mov_b32_e32 v137, v113
	s_add_i32 s55, s30, 0xffffff00
	s_or_b32 s94, s51, 0x100
	s_add_i32 s95, s30, 0xffffff80
	s_or_b32 s68, s51, 0x180
	s_mov_b32 s5, 0
	s_mov_b64 s[2:3], -1
	v_add_u32_e32 v131, 0, v2
	v_mov_b32_e32 v1, 0
	v_mov_b64_e32 v[2:3], 0
	v_mov_b64_e32 v[4:5], 0
	v_mov_b64_e32 v[6:7], 0
	v_mov_b64_e32 v[8:9], 0
	v_mov_b64_e32 v[10:11], 0
	v_mov_b64_e32 v[12:13], 0
	v_mov_b64_e32 v[14:15], 0
	v_mov_b64_e32 v[16:17], 0
	v_mov_b64_e32 v[18:19], 0
	v_mov_b64_e32 v[20:21], 0
	v_mov_b64_e32 v[22:23], 0
	v_mov_b64_e32 v[24:25], 0
	v_mov_b64_e32 v[26:27], 0
	v_mov_b64_e32 v[28:29], 0
	v_mov_b64_e32 v[30:31], 0
	v_mov_b64_e32 v[32:33], 0
	v_mov_b64_e32 v[34:35], 0
	v_mov_b64_e32 v[36:37], 0
	v_mov_b64_e32 v[38:39], 0
	v_mov_b64_e32 v[40:41], 0
	v_mov_b64_e32 v[42:43], 0
	v_mov_b64_e32 v[44:45], 0
	v_mov_b64_e32 v[46:47], 0
	v_mov_b64_e32 v[64:65], 0
	v_mov_b64_e32 v[66:67], 0
	v_mov_b64_e32 v[80:81], 0
	v_mov_b64_e32 v[82:83], 0
	v_mov_b64_e32 v[96:97], 0
	v_mov_b64_e32 v[98:99], 0
	v_mov_b64_e32 v[100:101], 0
	v_mov_b64_e32 v[102:103], 0
	v_mov_b64_e32 v[104:105], 0
	v_mov_b64_e32 v[106:107], 0
	v_mov_b64_e32 v[108:109], 0
	v_mov_b64_e32 v[110:111], 0
	v_mov_b64_e32 v[114:115], 0
	v_mov_b64_e32 v[116:117], 0
	v_mov_b64_e32 v[118:119], 0
	v_mov_b64_e32 v[120:121], 0
	v_mov_b64_e32 v[122:123], 0
	v_mov_b64_e32 v[124:125], 0
	v_mov_b64_e32 v[126:127], 0
	v_mov_b64_e32 v[128:129], 0
	v_mov_b64_e32 v[48:49], 0
	v_mov_b64_e32 v[50:51], 0
	v_mov_b64_e32 v[52:53], 0
	v_mov_b64_e32 v[54:55], 0
	v_mov_b64_e32 v[56:57], 0
	v_mov_b64_e32 v[58:59], 0
	v_mov_b64_e32 v[60:61], 0
	v_mov_b64_e32 v[62:63], 0
	v_mov_b64_e32 v[68:69], 0
	v_mov_b64_e32 v[70:71], 0
	v_mov_b64_e32 v[72:73], 0
	v_mov_b64_e32 v[74:75], 0
	v_mov_b64_e32 v[76:77], 0
	v_mov_b64_e32 v[78:79], 0
	v_mov_b64_e32 v[84:85], 0
	v_mov_b64_e32 v[86:87], 0
	v_mov_b64_e32 v[88:89], 0
	v_mov_b64_e32 v[90:91], 0
	v_mov_b64_e32 v[92:93], 0
	v_mov_b64_e32 v[94:95], 0
	s_barrier

.LBB0_555:
	s_lshl_b32 s25, s25, 12
	s_add_i32 m0, s31, 0x18000
	v_lshl_add_u64 v[8:9], v[8:9], 0, s[36:37]
	s_lshl_b32 s24, s24, 13
	s_and_b32 s25, s25, 0x3000
	s_waitcnt vmcnt(2)
	s_barrier
	global_load_lds_dwordx4 v[8:9], off
	v_lshl_add_u64 v[6:7], v[6:7], 0, s[36:37]
	s_add_i32 m0, s31, 0x1a000
	s_add_i32 s46, s31, 0x8000
	s_add_i32 s47, s31, 0xa000
	global_load_lds_dwordx4 v[6:7], off
	v_lshl_add_u64 v[4:5], v[4:5], 0, s[36:37]
	s_mov_b32 m0, s46
	s_add_u32 s8, s8, 0x40080
	global_load_lds_dwordx4 v[4:5], off
	v_lshl_add_u64 v[2:3], v[2:3], 0, s[36:37]
	s_mov_b32 m0, s47
	s_addc_u32 s9, s9, 0
	global_load_lds_dwordx4 v[2:3], off
	s_add_i32 m0, s31, 0x1c000
	v_lshl_add_u64 v[2:3], s[8:9], 0, v[112:113]
	global_load_lds_dwordx4 v[2:3], off
	v_lshl_add_u64 v[0:1], s[8:9], 0, v[0:1]
	s_add_i32 m0, s31, 0x1e000
	v_readlane_b32 s8, v252, 11
	global_load_lds_dwordx4 v[0:1], off
	v_lshlrev_b32_e32 v0, 13, v18
	v_and_b32_e32 v0, 0x7fffc000, v0
	v_lshl_add_u32 v0, v19, 10, v0
	v_or_b32_e32 v0, v0, v20
	v_add_lshl_u32 v112, v0, v21, 1
	v_lshlrev_b32_e32 v0, 13, v22
	v_and_b32_e32 v0, 0x7fffc000, v0
	v_readlane_b32 s9, v252, 12
	s_add_u32 s6, s8, s6
	v_lshl_add_u32 v0, v23, 10, v0
	s_addc_u32 s7, s9, s7
	v_or_b32_e32 v0, v0, v24
	v_lshl_add_u64 v[134:135], s[6:7], 0, v[112:113]
	v_add_lshl_u32 v112, v0, v25, 1
	v_lshlrev_b32_e32 v0, 13, v10
	v_and_b32_e32 v0, 0x7fffc000, v0
	v_lshl_add_u32 v0, v11, 10, v0
	v_or_b32_e32 v0, v0, v12
	v_lshl_add_u64 v[136:137], s[6:7], 0, v[112:113]
	v_add_lshl_u32 v112, v0, v13, 1
	v_lshlrev_b32_e32 v0, 13, v14
	v_and_b32_e32 v27, 15, v26
	v_and_b32_e32 v0, 0x7fffc000, v0
	v_and_b32_e32 v28, 48, v26
	v_lshlrev_b32_e32 v27, 6, v27
	v_lshlrev_b32_e32 v26, 2, v26
	v_lshl_add_u32 v0, v15, 10, v0
	v_or_b32_e32 v29, v27, v28
	v_and_b32_e32 v26, 32, v26
	s_waitcnt vmcnt(6)
	v_or_b32_e32 v0, v0, v16
	v_bitop3_b32 v27, v27, v26, v28 bitop3:0x36
	v_bitop3_b32 v26, v29, s24, v26 bitop3:0xde
	v_lshl_add_u64 v[138:139], s[4:5], 0, v[112:113]
	v_add_lshl_u32 v112, v0, v17, 1
	v_mov_b32_e32 v0, 0
	v_or_b32_e32 v142, s25, v27
	v_lshl_add_u64 v[140:141], s[4:5], 0, v[112:113]
	s_mov_b32 s4, -2
	v_add_u32_e32 v112, 0, v26
	v_mov_b32_e32 v1, 0
	v_mov_b64_e32 v[2:3], 0
	v_mov_b64_e32 v[4:5], 0
	v_mov_b64_e32 v[6:7], 0
	v_mov_b64_e32 v[8:9], 0
	v_mov_b64_e32 v[10:11], 0
	v_mov_b64_e32 v[12:13], 0
	v_mov_b64_e32 v[14:15], 0
	v_mov_b64_e32 v[16:17], 0
	v_mov_b64_e32 v[18:19], 0
	v_mov_b64_e32 v[20:21], 0
	v_mov_b64_e32 v[22:23], 0
	v_mov_b64_e32 v[24:25], 0
	v_mov_b64_e32 v[26:27], 0
	v_mov_b64_e32 v[28:29], 0
	v_mov_b64_e32 v[30:31], 0
	v_mov_b64_e32 v[32:33], 0
	v_mov_b64_e32 v[34:35], 0
	v_mov_b64_e32 v[36:37], 0
	v_mov_b64_e32 v[38:39], 0
	v_mov_b64_e32 v[40:41], 0
	v_mov_b64_e32 v[42:43], 0
	v_mov_b64_e32 v[44:45], 0
	v_mov_b64_e32 v[46:47], 0
	v_mov_b64_e32 v[48:49], 0
	v_mov_b64_e32 v[50:51], 0
	v_mov_b64_e32 v[52:53], 0
	v_mov_b64_e32 v[54:55], 0
	v_mov_b64_e32 v[56:57], 0
	v_mov_b64_e32 v[58:59], 0
	v_mov_b64_e32 v[60:61], 0
	v_mov_b64_e32 v[62:63], 0
	v_mov_b64_e32 v[68:69], 0
	v_mov_b64_e32 v[70:71], 0
	v_mov_b64_e32 v[80:81], 0
	v_mov_b64_e32 v[82:83], 0
	v_mov_b64_e32 v[84:85], 0
	v_mov_b64_e32 v[86:87], 0
	v_mov_b64_e32 v[88:89], 0
	v_mov_b64_e32 v[90:91], 0
	v_mov_b64_e32 v[92:93], 0
	v_mov_b64_e32 v[94:95], 0
	v_mov_b64_e32 v[96:97], 0
	v_mov_b64_e32 v[98:99], 0
	v_mov_b64_e32 v[100:101], 0
	v_mov_b64_e32 v[102:103], 0
	v_mov_b64_e32 v[104:105], 0
	v_mov_b64_e32 v[106:107], 0
	v_mov_b64_e32 v[108:109], 0
	v_mov_b64_e32 v[110:111], 0
	v_mov_b64_e32 v[114:115], 0
	v_mov_b64_e32 v[116:117], 0
	v_mov_b64_e32 v[118:119], 0
	v_mov_b64_e32 v[120:121], 0
	v_mov_b64_e32 v[122:123], 0
	v_mov_b64_e32 v[124:125], 0
	v_mov_b64_e32 v[126:127], 0
	v_mov_b64_e32 v[128:129], 0
	v_mov_b64_e32 v[64:65], 0
	v_mov_b64_e32 v[66:67], 0
	v_mov_b64_e32 v[72:73], 0
	v_mov_b64_e32 v[74:75], 0
	v_mov_b64_e32 v[76:77], 0
	v_mov_b64_e32 v[78:79], 0
	s_barrier

.LBB0_830:
	s_ashr_i32 s49, s48, 31
	s_lshl_b64 s[0:1], s[48:49], 19
	s_add_u32 s0, s26, s0
	s_addc_u32 s1, s27, s1
	s_and_b64 s[6:7], s[2:3], exec
	s_cselect_b32 s5, s1, s51
	s_cselect_b32 s49, s0, s50
	s_ashr_i32 s39, s38, 31
	s_lshl_b64 s[6:7], s[38:39], 19
	v_readlane_b32 s24, v254, 5
	v_readlane_b32 s25, v254, 6
	s_add_u32 s6, s24, s6
	s_addc_u32 s7, s25, s7
	s_and_b64 s[24:25], s[2:3], exec
	s_cselect_b32 s39, s7, s13
	s_cselect_b32 s54, s6, s12
	s_add_u32 vcc_lo, s50, 0x40080
	s_addc_u32 vcc_hi, s51, 0
	s_add_u32 s55, s12, 0x100
	v_mov_b32_e32 v0, 0
	s_addc_u32 s68, s13, 0
	s_mov_b32 s69, -2
	v_mov_b32_e32 v1, 0
	v_mov_b64_e32 v[2:3], 0
	v_mov_b64_e32 v[4:5], 0
	v_mov_b64_e32 v[6:7], 0
	v_mov_b64_e32 v[16:17], 0
	v_mov_b64_e32 v[18:19], 0
	v_mov_b64_e32 v[20:21], 0
	v_mov_b64_e32 v[22:23], 0
	v_mov_b64_e32 v[32:33], 0
	v_mov_b64_e32 v[34:35], 0
	v_mov_b64_e32 v[36:37], 0
	v_mov_b64_e32 v[38:39], 0
	v_mov_b64_e32 v[48:49], 0
	v_mov_b64_e32 v[50:51], 0
	v_mov_b64_e32 v[52:53], 0
	v_mov_b64_e32 v[54:55], 0
	v_mov_b64_e32 v[8:9], 0
	v_mov_b64_e32 v[10:11], 0
	v_mov_b64_e32 v[12:13], 0
	v_mov_b64_e32 v[14:15], 0
	v_mov_b64_e32 v[24:25], 0
	v_mov_b64_e32 v[26:27], 0
	v_mov_b64_e32 v[28:29], 0
	v_mov_b64_e32 v[30:31], 0
	v_mov_b64_e32 v[40:41], 0
	v_mov_b64_e32 v[42:43], 0
	v_mov_b64_e32 v[44:45], 0
	v_mov_b64_e32 v[46:47], 0
	v_mov_b64_e32 v[56:57], 0
	v_mov_b64_e32 v[58:59], 0
	v_mov_b64_e32 v[60:61], 0
	v_mov_b64_e32 v[62:63], 0
	v_mov_b64_e32 v[64:65], 0
	v_mov_b64_e32 v[66:67], 0
	v_mov_b64_e32 v[68:69], 0
	v_mov_b64_e32 v[70:71], 0
	v_mov_b64_e32 v[80:81], 0
	v_mov_b64_e32 v[82:83], 0
	v_mov_b64_e32 v[84:85], 0
	v_mov_b64_e32 v[86:87], 0
	v_mov_b64_e32 v[96:97], 0
	v_mov_b64_e32 v[98:99], 0
	v_mov_b64_e32 v[100:101], 0
	v_mov_b64_e32 v[102:103], 0
	v_mov_b64_e32 v[114:115], 0
	v_mov_b64_e32 v[116:117], 0
	v_mov_b64_e32 v[118:119], 0
	v_mov_b64_e32 v[120:121], 0
	v_mov_b64_e32 v[72:73], 0
	v_mov_b64_e32 v[74:75], 0
	v_mov_b64_e32 v[76:77], 0
	v_mov_b64_e32 v[78:79], 0
	v_mov_b64_e32 v[88:89], 0
	v_mov_b64_e32 v[90:91], 0
	v_mov_b64_e32 v[92:93], 0
	v_mov_b64_e32 v[94:95], 0
	v_mov_b64_e32 v[104:105], 0
	v_mov_b64_e32 v[106:107], 0
	v_mov_b64_e32 v[108:109], 0
	v_mov_b64_e32 v[110:111], 0
	v_mov_b64_e32 v[122:123], 0
	v_mov_b64_e32 v[124:125], 0
	v_mov_b64_e32 v[126:127], 0
	v_mov_b64_e32 v[128:129], 0

.LBB0_986:
	s_ashr_i32 s49, s48, 31
	s_lshl_b64 s[0:1], s[48:49], 19
	s_add_u32 s0, s26, s0
	s_addc_u32 s1, s27, s1
	s_and_b64 s[6:7], s[2:3], exec
	s_cselect_b32 s5, s1, s51
	s_cselect_b32 s49, s0, s50
	s_ashr_i32 s39, s38, 31
	s_lshl_b64 s[6:7], s[38:39], 19
	v_readlane_b32 s24, v254, 7
	v_readlane_b32 s25, v254, 8
	s_add_u32 s6, s24, s6
	s_addc_u32 s7, s25, s7
	s_and_b64 s[24:25], s[2:3], exec
	s_cselect_b32 s39, s7, s13
	s_cselect_b32 s54, s6, s12
	s_add_u32 vcc_lo, s50, 0x40080
	s_addc_u32 vcc_hi, s51, 0
	s_add_u32 s55, s12, 0x100
	v_mov_b32_e32 v0, 0
	s_addc_u32 s68, s13, 0
	s_mov_b32 s69, -2
	v_mov_b32_e32 v1, 0
	v_mov_b64_e32 v[2:3], 0
	v_mov_b64_e32 v[4:5], 0
	v_mov_b64_e32 v[6:7], 0
	v_mov_b64_e32 v[16:17], 0
	v_mov_b64_e32 v[18:19], 0
	v_mov_b64_e32 v[20:21], 0
	v_mov_b64_e32 v[22:23], 0
	v_mov_b64_e32 v[32:33], 0
	v_mov_b64_e32 v[34:35], 0
	v_mov_b64_e32 v[36:37], 0
	v_mov_b64_e32 v[38:39], 0
	v_mov_b64_e32 v[48:49], 0
	v_mov_b64_e32 v[50:51], 0
	v_mov_b64_e32 v[52:53], 0
	v_mov_b64_e32 v[54:55], 0
	v_mov_b64_e32 v[8:9], 0
	v_mov_b64_e32 v[10:11], 0
	v_mov_b64_e32 v[12:13], 0
	v_mov_b64_e32 v[14:15], 0
	v_mov_b64_e32 v[24:25], 0
	v_mov_b64_e32 v[26:27], 0
	v_mov_b64_e32 v[28:29], 0
	v_mov_b64_e32 v[30:31], 0
	v_mov_b64_e32 v[40:41], 0
	v_mov_b64_e32 v[42:43], 0
	v_mov_b64_e32 v[44:45], 0
	v_mov_b64_e32 v[46:47], 0
	v_mov_b64_e32 v[56:57], 0
	v_mov_b64_e32 v[58:59], 0
	v_mov_b64_e32 v[60:61], 0
	v_mov_b64_e32 v[62:63], 0
	v_mov_b64_e32 v[64:65], 0
	v_mov_b64_e32 v[66:67], 0
	v_mov_b64_e32 v[68:69], 0
	v_mov_b64_e32 v[70:71], 0
	v_mov_b64_e32 v[80:81], 0
	v_mov_b64_e32 v[82:83], 0
	v_mov_b64_e32 v[84:85], 0
	v_mov_b64_e32 v[86:87], 0
	v_mov_b64_e32 v[96:97], 0
	v_mov_b64_e32 v[98:99], 0
	v_mov_b64_e32 v[100:101], 0
	v_mov_b64_e32 v[102:103], 0
	v_mov_b64_e32 v[114:115], 0
	v_mov_b64_e32 v[116:117], 0
	v_mov_b64_e32 v[118:119], 0
	v_mov_b64_e32 v[120:121], 0
	v_mov_b64_e32 v[72:73], 0
	v_mov_b64_e32 v[74:75], 0
	v_mov_b64_e32 v[76:77], 0
	v_mov_b64_e32 v[78:79], 0
	v_mov_b64_e32 v[88:89], 0
	v_mov_b64_e32 v[90:91], 0
	v_mov_b64_e32 v[92:93], 0
	v_mov_b64_e32 v[94:95], 0
	v_mov_b64_e32 v[104:105], 0
	v_mov_b64_e32 v[106:107], 0
	v_mov_b64_e32 v[108:109], 0
	v_mov_b64_e32 v[110:111], 0
	v_mov_b64_e32 v[122:123], 0
	v_mov_b64_e32 v[124:125], 0
	v_mov_b64_e32 v[126:127], 0
	v_mov_b64_e32 v[128:129], 0

.LBB0_1470:
	v_and_b32_e32 v27, 15, v26
	v_and_b32_e32 v28, 48, v26
	v_lshlrev_b32_e32 v27, 6, v27
	v_lshlrev_b32_e32 v26, 2, v26
	s_lshl_b32 s25, s25, 12
	s_add_i32 m0, s97, 0x18000
	v_lshl_add_u64 v[2:3], v[2:3], 0, s[36:37]
	v_or_b32_e32 v29, v27, v28
	v_and_b32_e32 v26, 32, v26
	s_lshl_b32 s24, s24, 13
	s_and_b32 s25, s25, 0x3000
	s_waitcnt vmcnt(2)
	s_barrier
	global_load_lds_dwordx4 v[2:3], off
	v_lshl_add_u64 v[2:3], v[4:5], 0, s[36:37]
	s_add_i32 m0, s97, 0x1a000
	s_add_i32 s54, s97, 0x8000
	s_add_i32 s55, s97, 0xa000
	v_bitop3_b32 v27, v27, v26, v28 bitop3:0x36
	v_bitop3_b32 v26, v29, s24, v26 bitop3:0xde
	global_load_lds_dwordx4 v[2:3], off
	v_lshl_add_u64 v[2:3], v[6:7], 0, s[36:37]
	s_mov_b32 m0, s54
	s_add_u32 s24, s48, 0x40080
	v_or_b32_e32 v142, s25, v27
	global_load_lds_dwordx4 v[2:3], off
	v_lshl_add_u64 v[2:3], v[8:9], 0, s[36:37]
	s_mov_b32 m0, s55
	s_addc_u32 s25, s49, 0
	global_load_lds_dwordx4 v[2:3], off
	s_add_i32 m0, s97, 0x1c000
	v_lshl_add_u64 v[2:3], s[24:25], 0, v[112:113]
	global_load_lds_dwordx4 v[2:3], off
	v_lshl_add_u64 v[0:1], s[24:25], 0, v[0:1]
	s_add_i32 m0, s97, 0x1e000
	s_add_i32 s48, s10, -2
	global_load_lds_dwordx4 v[0:1], off
	v_lshlrev_b32_e32 v0, 13, v18
	v_and_b32_e32 v0, 0x7fffc000, v0
	v_lshl_add_u32 v0, v19, 10, v0
	v_or_b32_e32 v0, v0, v20
	v_add_lshl_u32 v112, v0, v22, 1
	v_lshlrev_b32_e32 v0, 13, v21
	v_and_b32_e32 v0, 0x7fffc000, v0
	s_add_u32 s24, s31, s38
	v_lshl_add_u32 v0, v23, 10, v0
	s_addc_u32 s25, s47, s39
	v_or_b32_e32 v0, v0, v24
	v_lshl_add_u64 v[134:135], s[24:25], 0, v[112:113]
	v_add_lshl_u32 v112, v0, v25, 1
	v_lshlrev_b32_e32 v0, 13, v10
	v_and_b32_e32 v0, 0x7fffc000, v0
	v_lshl_add_u32 v0, v11, 10, v0
	v_or_b32_e32 v0, v0, v12
	v_lshl_add_u64 v[136:137], s[24:25], 0, v[112:113]
	v_add_lshl_u32 v112, v0, v13, 1
	v_lshlrev_b32_e32 v0, 13, v14
	v_and_b32_e32 v0, 0x7fffc000, v0
	s_add_u32 s12, s78, s12
	v_lshl_add_u32 v0, v15, 10, v0
	s_waitcnt vmcnt(6)
	s_addc_u32 s13, s79, s13
	v_or_b32_e32 v0, v0, v16
	v_lshl_add_u64 v[138:139], s[12:13], 0, v[112:113]
	v_add_lshl_u32 v112, v0, v17, 1
	v_mov_b32_e32 v0, 0
	v_lshl_add_u64 v[140:141], s[12:13], 0, v[112:113]
	s_mov_b32 s12, 0
	v_add_u32_e32 v112, 0, v26
	v_mov_b32_e32 v1, 0
	v_mov_b64_e32 v[2:3], 0
	v_mov_b64_e32 v[4:5], 0
	v_mov_b64_e32 v[6:7], 0
	v_mov_b64_e32 v[8:9], 0
	v_mov_b64_e32 v[10:11], 0
	v_mov_b64_e32 v[12:13], 0
	v_mov_b64_e32 v[14:15], 0
	v_mov_b64_e32 v[16:17], 0
	v_mov_b64_e32 v[18:19], 0
	v_mov_b64_e32 v[20:21], 0
	v_mov_b64_e32 v[22:23], 0
	v_mov_b64_e32 v[24:25], 0
	v_mov_b64_e32 v[26:27], 0
	v_mov_b64_e32 v[28:29], 0
	v_mov_b64_e32 v[30:31], 0
	v_mov_b64_e32 v[32:33], 0
	v_mov_b64_e32 v[34:35], 0
	v_mov_b64_e32 v[36:37], 0
	v_mov_b64_e32 v[38:39], 0
	v_mov_b64_e32 v[40:41], 0
	v_mov_b64_e32 v[42:43], 0
	v_mov_b64_e32 v[44:45], 0
	v_mov_b64_e32 v[46:47], 0
	v_mov_b64_e32 v[48:49], 0
	v_mov_b64_e32 v[50:51], 0
	v_mov_b64_e32 v[52:53], 0
	v_mov_b64_e32 v[54:55], 0
	v_mov_b64_e32 v[56:57], 0
	v_mov_b64_e32 v[58:59], 0
	v_mov_b64_e32 v[60:61], 0
	v_mov_b64_e32 v[62:63], 0
	v_mov_b64_e32 v[68:69], 0
	v_mov_b64_e32 v[70:71], 0
	v_mov_b64_e32 v[80:81], 0
	v_mov_b64_e32 v[82:83], 0
	v_mov_b64_e32 v[84:85], 0
	v_mov_b64_e32 v[86:87], 0
	v_mov_b64_e32 v[88:89], 0
	v_mov_b64_e32 v[90:91], 0
	v_mov_b64_e32 v[92:93], 0
	v_mov_b64_e32 v[94:95], 0
	v_mov_b64_e32 v[96:97], 0
	v_mov_b64_e32 v[98:99], 0
	v_mov_b64_e32 v[100:101], 0
	v_mov_b64_e32 v[102:103], 0
	v_mov_b64_e32 v[104:105], 0
	v_mov_b64_e32 v[106:107], 0
	v_mov_b64_e32 v[108:109], 0
	v_mov_b64_e32 v[110:111], 0
	v_mov_b64_e32 v[114:115], 0
	v_mov_b64_e32 v[116:117], 0
	v_mov_b64_e32 v[118:119], 0
	v_mov_b64_e32 v[120:121], 0
	v_mov_b64_e32 v[122:123], 0
	v_mov_b64_e32 v[124:125], 0
	v_mov_b64_e32 v[126:127], 0
	v_mov_b64_e32 v[128:129], 0
	v_mov_b64_e32 v[64:65], 0
	v_mov_b64_e32 v[66:67], 0
	v_mov_b64_e32 v[72:73], 0
	v_mov_b64_e32 v[74:75], 0
	v_mov_b64_e32 v[76:77], 0
	v_mov_b64_e32 v[78:79], 0
	s_barrier

.LBB0_1755:
	s_ashr_i32 s9, s8, 31
	s_lshl_b64 s[24:25], s[8:9], 19
	s_add_u32 s38, s26, s24
	s_addc_u32 s39, s27, s25
	s_and_b64 s[24:25], s[2:3], exec
	s_cselect_b32 s9, s39, s51
	s_cselect_b32 s54, s38, s50
	s_ashr_i32 s7, s6, 31
	s_lshl_b64 s[24:25], s[6:7], 19
	s_add_u32 s48, s10, s24
	s_addc_u32 s49, s14, s25
	s_and_b64 s[24:25], s[2:3], exec
	s_cselect_b32 s7, s49, s13
	s_cselect_b32 s55, s48, s12
	s_add_u32 vcc_lo, s50, 0x40080
	s_addc_u32 vcc_hi, s51, 0
	s_add_u32 s68, s12, 0x100
	v_mov_b32_e32 v0, 0
	s_mov_b32 s60, s94
	s_addc_u32 s69, s13, 0
	s_mov_b32 s94, -2
	v_mov_b32_e32 v1, 0
	v_mov_b64_e32 v[2:3], 0
	v_mov_b64_e32 v[8:9], 0
	v_mov_b64_e32 v[10:11], 0
	v_mov_b64_e32 v[16:17], 0
	v_mov_b64_e32 v[18:19], 0
	v_mov_b64_e32 v[24:25], 0
	v_mov_b64_e32 v[26:27], 0
	v_mov_b64_e32 v[32:33], 0
	v_mov_b64_e32 v[34:35], 0
	v_mov_b64_e32 v[40:41], 0
	v_mov_b64_e32 v[42:43], 0
	v_mov_b64_e32 v[48:49], 0
	v_mov_b64_e32 v[50:51], 0
	v_mov_b64_e32 v[56:57], 0
	v_mov_b64_e32 v[58:59], 0
	v_mov_b64_e32 v[4:5], 0
	v_mov_b64_e32 v[6:7], 0
	v_mov_b64_e32 v[12:13], 0
	v_mov_b64_e32 v[14:15], 0
	v_mov_b64_e32 v[20:21], 0
	v_mov_b64_e32 v[22:23], 0
	v_mov_b64_e32 v[28:29], 0
	v_mov_b64_e32 v[30:31], 0
	v_mov_b64_e32 v[36:37], 0
	v_mov_b64_e32 v[38:39], 0
	v_mov_b64_e32 v[44:45], 0
	v_mov_b64_e32 v[46:47], 0
	v_mov_b64_e32 v[52:53], 0
	v_mov_b64_e32 v[54:55], 0
	v_mov_b64_e32 v[60:61], 0
	v_mov_b64_e32 v[62:63], 0
	v_mov_b64_e32 v[64:65], 0
	v_mov_b64_e32 v[66:67], 0
	v_mov_b64_e32 v[72:73], 0
	v_mov_b64_e32 v[74:75], 0
	v_mov_b64_e32 v[80:81], 0
	v_mov_b64_e32 v[82:83], 0
	v_mov_b64_e32 v[88:89], 0
	v_mov_b64_e32 v[90:91], 0
	v_mov_b64_e32 v[96:97], 0
	v_mov_b64_e32 v[98:99], 0
	v_mov_b64_e32 v[104:105], 0
	v_mov_b64_e32 v[106:107], 0
	v_mov_b64_e32 v[114:115], 0
	v_mov_b64_e32 v[116:117], 0
	v_mov_b64_e32 v[122:123], 0
	v_mov_b64_e32 v[124:125], 0
	v_mov_b64_e32 v[68:69], 0
	v_mov_b64_e32 v[70:71], 0
	v_mov_b64_e32 v[76:77], 0
	v_mov_b64_e32 v[78:79], 0
	v_mov_b64_e32 v[84:85], 0
	v_mov_b64_e32 v[86:87], 0
	v_mov_b64_e32 v[92:93], 0
	v_mov_b64_e32 v[94:95], 0
	v_mov_b64_e32 v[100:101], 0
	v_mov_b64_e32 v[102:103], 0
	v_mov_b64_e32 v[108:109], 0
	v_mov_b64_e32 v[110:111], 0
	v_mov_b64_e32 v[118:119], 0
	v_mov_b64_e32 v[120:121], 0
	v_mov_b64_e32 v[126:127], 0
	v_mov_b64_e32 v[128:129], 0

.LBB0_1823:
	v_and_b32_e32 v27, 15, v26
	v_and_b32_e32 v28, 48, v26
	v_lshlrev_b32_e32 v26, 2, v26
	v_lshlrev_b32_e32 v27, 6, v27
	v_and_b32_e32 v26, 32, v26
	s_lshl_b32 s54, s54, 12
	v_or_b32_e32 v29, v27, v28
	v_bitop3_b32 v27, v27, v26, v28 bitop3:0x36
	s_and_b32 s54, s54, 0x3000
	s_add_i32 m0, s49, 0x18000
	v_lshl_add_u64 v[2:3], v[2:3], 0, s[36:37]
	s_lshl_b32 s52, s52, 13
	s_waitcnt vmcnt(0)
	v_or_b32_e32 v142, s54, v27
	s_waitcnt vmcnt(2)
	s_barrier
	global_load_lds_dwordx4 v[2:3], off
	v_lshl_add_u64 v[2:3], v[4:5], 0, s[36:37]
	s_add_i32 m0, s49, 0x1a000
	s_add_i32 s54, s49, 0x8000
	s_add_i32 s55, s49, 0xa000
	global_load_lds_dwordx4 v[2:3], off
	v_lshl_add_u64 v[2:3], v[6:7], 0, s[36:37]
	s_mov_b32 m0, s54
	s_add_u32 s8, s8, 0xb0080
	global_load_lds_dwordx4 v[2:3], off
	v_lshl_add_u64 v[2:3], v[8:9], 0, s[36:37]
	s_mov_b32 m0, s55
	s_addc_u32 s9, s9, 0
	global_load_lds_dwordx4 v[2:3], off
	s_add_i32 m0, s49, 0x1c000
	v_lshl_add_u64 v[2:3], s[8:9], 0, v[112:113]
	global_load_lds_dwordx4 v[2:3], off
	v_lshl_add_u64 v[0:1], s[8:9], 0, v[0:1]
	s_add_i32 m0, s49, 0x1e000
	s_add_i32 s8, s10, -2
	global_load_lds_dwordx4 v[0:1], off
	v_readlane_b32 s56, v252, 9
	v_readlane_b32 s57, v252, 10
	s_add_u32 s9, s56, s53
	s_addc_u32 s53, s57, s58
	s_movk_i32 s56, 0xb00
	v_bitop3_b32 v26, v29, s52, v26 bitop3:0xde
	s_add_u32 s52, s9, s6
	v_lshrrev_b32_e32 v1, 1, v18
	v_mul_lo_u32 v0, v20, s56
	s_mov_b32 s9, 0xb000
	v_mad_u64_u32 v[0:1], s[58:59], v1, s9, v[0:1]
	v_or_b32_e32 v0, v0, v19
	v_add_lshl_u32 v112, v0, v21, 1
	v_lshrrev_b32_e32 v1, 1, v22
	v_mul_lo_u32 v0, v23, s56
	v_mad_u64_u32 v[0:1], s[58:59], v1, s9, v[0:1]
	s_addc_u32 s53, s53, s7
	v_or_b32_e32 v0, v0, v24
	v_lshl_add_u64 v[134:135], s[52:53], 0, v[112:113]
	v_add_lshl_u32 v112, v0, v25, 1
	s_add_u32 s6, s24, s6
	v_lshrrev_b32_e32 v1, 1, v10
	v_mul_lo_u32 v0, v11, s56
	s_addc_u32 s7, s25, s7
	v_mad_u64_u32 v[0:1], s[24:25], v1, s9, v[0:1]
	v_or_b32_e32 v0, v0, v12
	v_lshl_add_u64 v[136:137], s[52:53], 0, v[112:113]
	v_add_lshl_u32 v112, v0, v13, 1
	v_lshrrev_b32_e32 v1, 1, v14
	v_mul_lo_u32 v0, v16, s56
	v_mad_u64_u32 v[0:1], s[24:25], v1, s9, v[0:1]
	s_waitcnt vmcnt(6)
	v_or_b32_e32 v0, v0, v15
	v_lshl_add_u64 v[138:139], s[6:7], 0, v[112:113]
	v_add_lshl_u32 v112, v0, v17, 1
	v_mov_b32_e32 v0, 0
	v_lshl_add_u64 v[140:141], s[6:7], 0, v[112:113]
	s_mov_b32 s6, 0
	v_add_u32_e32 v112, 0, v26
	v_mov_b32_e32 v1, 0
	v_mov_b64_e32 v[2:3], 0
	v_mov_b64_e32 v[4:5], 0
	v_mov_b64_e32 v[6:7], 0
	v_mov_b64_e32 v[8:9], 0
	v_mov_b64_e32 v[10:11], 0
	v_mov_b64_e32 v[12:13], 0
	v_mov_b64_e32 v[14:15], 0
	v_mov_b64_e32 v[16:17], 0
	v_mov_b64_e32 v[18:19], 0
	v_mov_b64_e32 v[20:21], 0
	v_mov_b64_e32 v[22:23], 0
	v_mov_b64_e32 v[24:25], 0
	v_mov_b64_e32 v[26:27], 0
	v_mov_b64_e32 v[28:29], 0
	v_mov_b64_e32 v[30:31], 0
	v_mov_b64_e32 v[32:33], 0
	v_mov_b64_e32 v[34:35], 0
	v_mov_b64_e32 v[36:37], 0
	v_mov_b64_e32 v[38:39], 0
	v_mov_b64_e32 v[40:41], 0
	v_mov_b64_e32 v[42:43], 0
	v_mov_b64_e32 v[44:45], 0
	v_mov_b64_e32 v[46:47], 0
	v_mov_b64_e32 v[48:49], 0
	v_mov_b64_e32 v[50:51], 0
	v_mov_b64_e32 v[52:53], 0
	v_mov_b64_e32 v[54:55], 0
	v_mov_b64_e32 v[56:57], 0
	v_mov_b64_e32 v[58:59], 0
	v_mov_b64_e32 v[60:61], 0
	v_mov_b64_e32 v[62:63], 0
	v_mov_b64_e32 v[68:69], 0
	v_mov_b64_e32 v[70:71], 0
	v_mov_b64_e32 v[80:81], 0
	v_mov_b64_e32 v[82:83], 0
	v_mov_b64_e32 v[84:85], 0
	v_mov_b64_e32 v[86:87], 0
	v_mov_b64_e32 v[88:89], 0
	v_mov_b64_e32 v[90:91], 0
	v_mov_b64_e32 v[92:93], 0
	v_mov_b64_e32 v[94:95], 0
	v_mov_b64_e32 v[96:97], 0
	v_mov_b64_e32 v[98:99], 0
	v_mov_b64_e32 v[100:101], 0
	v_mov_b64_e32 v[102:103], 0
	v_mov_b64_e32 v[104:105], 0
	v_mov_b64_e32 v[106:107], 0
	v_mov_b64_e32 v[108:109], 0
	v_mov_b64_e32 v[110:111], 0
	v_mov_b64_e32 v[114:115], 0
	v_mov_b64_e32 v[116:117], 0
	v_mov_b64_e32 v[118:119], 0
	v_mov_b64_e32 v[120:121], 0
	v_mov_b64_e32 v[122:123], 0
	v_mov_b64_e32 v[124:125], 0
	v_mov_b64_e32 v[126:127], 0
	v_mov_b64_e32 v[128:129], 0
	v_mov_b64_e32 v[64:65], 0
	v_mov_b64_e32 v[66:67], 0
	v_mov_b64_e32 v[72:73], 0
	v_mov_b64_e32 v[74:75], 0
	v_mov_b64_e32 v[76:77], 0
	v_mov_b64_e32 v[78:79], 0
	s_barrier
